# attention: rewrote per-tile K/V DMA issue (ISSUE_TILE) as branch-free code: precomputed per-wave chunk-type mask, 30 instr instead of ~160 with 25 branches
# speedup vs baseline: 1.0066x; 1.0066x over previous
; #define LAS __attribute__((address_space(3)))
; __device__ __forceinline__ void attn_phase(const Ptrs& P, LAS unsigned char* lds, int vcu) {
;     const int tid = threadIdx.x, lane = tid & 63, wid = __builtin_amdgcn_readfirstlane(tid >> 6), r32 = lane & 31, hi = lane >> 5;
;     const bf16_t* QI = (const bf16_t*)(P.ws + WS_QIMG); const bf16_t* KN = (const bf16_t*)(P.ws + WS_RA); const bf16_t* KPE = (const bf16_t*)(P.ws + WS_KPE); const bf16_t* VI = (const bf16_t*)(P.ws + WS_VIMG);
;     bf16_t* A2 = (bf16_t*)(P.ws + WS_A2);
;     const int bh = vcu >> 1, b = bh >> 3, head = bh & 7;
;     const bf16_t* kn_b = KN + (size_t)bh * 64 * 4096 + lane * 8; const bf16_t* kpe_b = KPE + (size_t)b * 64 * 2048 + lane * 8; const bf16_t* v_b = VI + (size_t)bh * 256 * 1024 + lane * 8;
;     LAS unsigned char* const wz = lds + 2 * ATT_STAGE + wid * 8192;
;     const int vb = 24576 + (4 * hi + ((lane & 15) >> 2)) * 64 + ((lane >> 4) & 1) * 32 + (lane & 3) * 8;
.LBB0_1114:
	s_ashr_i32 s10, s87, 1
	s_ashr_i32 s12, s87, 4
	v_readfirstlane_b32 s16, v200
	s_ashr_i32 s11, s10, 31
	s_ashr_i32 s13, s12, 31
	s_lshr_b32 s17, s16, 6
	s_cmp_eq_u32 s17, 3
	s_cselect_b32 s32, 30, 0
	s_cmp_eq_u32 s17, 4
	s_cselect_b32 s32, 15, s32
	s_lshl_b64 s[2:3], s[10:11], 19
	s_lshl_b64 s[0:1], s[12:13], 18
	s_cmpk_lt_u32 s16, 0x100
	s_cselect_b64 s[6:7], -1, 0
	s_cmpk_gt_u32 s16, 0xff
	s_cselect_b64 s[76:77], -1, 0
	v_lshl_add_u64 v[2:3], v[180:181], 0, s[0:1]
	v_lshl_add_u64 v[188:189], v[182:183], 0, s[2:3]
	s_mov_b64 s[4:5], -1
	s_and_b64 vcc, exec, s[76:77]
	s_mul_i32 s20, s17, 0xa00
	s_cbranch_vccz .LBB0_1120
	s_cmpk_gt_u32 s16, 0x13f
	s_cbranch_scc0 .LBB0_1117
	s_add_i32 s72, s20, 0xffffd000
	v_lshl_add_u64 v[4:5], s[72:73], 1, v[188:189]
	s_mov_b64 s[4:5], 0

; __device__ __forceinline__ void attn_phase(const Ptrs& P, LAS unsigned char* lds, int vcu) {
;     ...
;             if (t + 1 < NT) ISSUE_TILE(t + 1, (t + 1) & 1); else if (ui + 1 < 4) ISSUE_TILE(0, 0);
;             if (64 * t <= qw) {
.LBB0_1177:
	s_lshl_b32 s6, s72, 14
	s_lshl_b32 s7, s72, 13
	s_mov_b32 s1, 0
	s_bitcmp1_b32 s72, 0
	s_cselect_b32 s9, 0xa000, 0
	s_bitcmp1_b32 s32, 0
	s_cselect_b32 s0, s7, s6
	s_add_i32 m0, s9, s33
	v_lshl_add_u64 v[2:3], v[192:193], 0, s[0:1]
	global_load_lds_dwordx4 v[2:3], off
	s_bitcmp1_b32 s32, 1
	s_cselect_b32 s0, s7, s6
	s_add_i32 m0, s9, s93
	v_lshl_add_u64 v[4:5], v[194:195], 0, s[0:1]
	global_load_lds_dwordx4 v[4:5], off
	s_bitcmp1_b32 s32, 2
	s_cselect_b32 s0, s7, s6
	s_add_i32 m0, s9, s91
	v_lshl_add_u64 v[6:7], v[196:197], 0, s[0:1]
	global_load_lds_dwordx4 v[6:7], off
	s_bitcmp1_b32 s32, 3
	s_cselect_b32 s0, s7, s6
	s_add_i32 m0, s9, s71
	v_lshl_add_u64 v[2:3], v[198:199], 0, s[0:1]
	global_load_lds_dwordx4 v[2:3], off
	s_bitcmp1_b32 s32, 4
	s_cselect_b32 s0, s7, s6
	s_add_i32 m0, s9, s75
	v_lshl_add_u64 v[4:5], v[202:203], 0, s[0:1]
	global_load_lds_dwordx4 v[4:5], off
	s_sub_i32 s0, s90, 63
	s_cmp_gt_u32 s0, s92
	s_cbranch_scc1 .LBB0_1229
